# LRU input-projection epilogue (rec branch): n=0 / n=1 halves of the conv output rows leave as one global_store_dwordx4 (16 stores per lane and tile instead of 32)
# baseline (speedup 1.0000x reference)
; #define LAS __attribute__((address_space(3)))
;     __device__ __forceinline__ void operator()(AccRef acc, const Unit& u, int wr, int wc, int fr, int fq) const {
;     ...
;         for (int bj = 0; bj < 2; ++bj)
; #pragma unroll
;             for (int n = 0; n < 2; ++n) {
;                 const int c0 = col0 + bj * 128 + 4 * n;
;                 const f32x4 w0 = *(const f32x4*)(cw + c0), w1 = *(const f32x4*)(cw + D + c0), w2 = *(const f32x4*)(cw + 2 * D + c0), w3 = *(const f32x4*)(cw + 3 * D + c0), bb = *(const f32x4*)(cb + c0);
; #pragma unroll
;                 for (int ai = 0; ai < 2; ++ai) {
;                     f32x4 h1 = (f32x4){0.f, 0.f, 0.f, 0.f}, h2 = h1, h3 = h1;
;                     const int pb = ai * 2 + wr - 1;
;                     if (pb >= 0 && fr == 0) { const LAS float* xp = xch + (pb * 3) * 256 + bj * 128 + clb + 4 * n; h1 = *(const LAS f32x4*)(xp); h2 = *(const LAS f32x4*)(xp + 256); h3 = *(const LAS f32x4*)(xp + 512); }
;                     float o[4][4];
; #pragma unroll
;                     for (int j = 0; j < 4; ++j) {
;                         const float v0 = acc[ai][bj][0][n][j], v1 = acc[ai][bj][1][n][j], v2 = acc[ai][bj][2][n][j], v3 = acc[ai][bj][3][n][j];
;                         const float p3 = dpp_upd<0x111>(h3[j], v3), p2 = dpp_upd<0x111>(h2[j], v2), p1 = dpp_upd<0x111>(h1[j], v1);
;                         o[0][j] = bb[j] + w3[j] * v0 + w2[j] * p3 + w1[j] * p2 + w0[j] * p1;
;                         o[1][j] = bb[j] + w3[j] * v1 + w2[j] * v0 + w1[j] * p3 + w0[j] * p2;
;                         o[2][j] = bb[j] + w3[j] * v2 + w2[j] * v1 + w1[j] * v0 + w0[j] * p3;
;                         o[3][j] = bb[j] + w3[j] * v3 + w2[j] * v2 + w1[j] * v1 + w0[j] * v0; }
; #pragma unroll
;                     for (int m = 0; m < 4; ++m) *(u32x2*)(REC + (size_t)(row0 + ai * 128 + m) * D + c0) = (u32x2){cvt_pk_bf16(o[m][0], o[m][1]), cvt_pk_bf16(o[m][2], o[m][3])};
;                 }
.LBB0_1000:
	s_or_b64 exec, exec, s[76:77]
	s_waitcnt lgkmcnt(0)
	v_mov_b32_dpp v150, v76 row_shr:1 row_mask:0xf bank_mask:0xf
	v_mov_b32_dpp v151, v77 row_shr:1 row_mask:0xf bank_mask:0xf
	s_waitcnt vmcnt(0)
	v_pk_fma_f32 v[184:185], v[124:125], v[140:141], v[144:145]
	v_mov_b32_dpp v154, v92 row_shr:1 row_mask:0xf bank_mask:0xf
	v_mov_b32_dpp v155, v93 row_shr:1 row_mask:0xf bank_mask:0xf
	v_pk_fma_f32 v[184:185], v[136:137], v[150:151], v[184:185]
	v_mov_b32_dpp v158, v108 row_shr:1 row_mask:0xf bank_mask:0xf
	v_mov_b32_dpp v159, v109 row_shr:1 row_mask:0xf bank_mask:0xf
	v_pk_fma_f32 v[184:185], v[128:129], v[154:155], v[184:185]
	v_mov_b32_dpp v152, v78 row_shr:1 row_mask:0xf bank_mask:0xf
	v_mov_b32_dpp v153, v79 row_shr:1 row_mask:0xf bank_mask:0xf
	v_pk_fma_f32 v[158:159], v[132:133], v[158:159], v[184:185]
	v_pk_fma_f32 v[184:185], v[126:127], v[142:143], v[146:147]
	v_mov_b32_dpp v156, v94 row_shr:1 row_mask:0xf bank_mask:0xf
	v_mov_b32_dpp v157, v95 row_shr:1 row_mask:0xf bank_mask:0xf
	v_pk_fma_f32 v[184:185], v[138:139], v[152:153], v[184:185]
	v_mov_b32_dpp v160, v110 row_shr:1 row_mask:0xf bank_mask:0xf
	v_mov_b32_dpp v161, v111 row_shr:1 row_mask:0xf bank_mask:0xf
	v_pk_fma_f32 v[184:185], v[130:131], v[156:157], v[184:185]
	v_ashrrev_i32_e32 v183, 31, v182
	v_pk_fma_f32 v[160:161], v[134:135], v[160:161], v[184:185]
	v_cvt_pk_bf16_f32 v158, v158, v159
	v_cvt_pk_bf16_f32 v159, v160, v161
	v_lshlrev_b64 v[160:161], 11, v[182:183]
	v_lshl_add_u64 v[160:161], s[18:19], 0, v[160:161]
	v_lshlrev_b32_e32 v170, 1, v220
	v_lshl_add_u64 v[184:185], v[160:161], 0, v[170:171]
	v_mov_b32_e32 v183, v158
	v_mov_b32_e32 v221, v159
	v_pk_fma_f32 v[158:159], v[108:109], v[140:141], v[144:145]
	v_mov_b32_e32 v149, 0
	v_pk_fma_f32 v[158:159], v[124:125], v[136:137], v[158:159]
	s_nop 0
	v_pk_fma_f32 v[158:159], v[128:129], v[150:151], v[158:159]
	s_nop 0
	v_pk_fma_f32 v[154:155], v[132:133], v[154:155], v[158:159]
	v_pk_fma_f32 v[158:159], v[110:111], v[142:143], v[146:147]
	v_cvt_pk_bf16_f32 v154, v154, v155
	v_pk_fma_f32 v[158:159], v[126:127], v[138:139], v[158:159]
	s_nop 0
	v_pk_fma_f32 v[158:159], v[130:131], v[152:153], v[158:159]
	s_nop 0
	v_pk_fma_f32 v[156:157], v[134:135], v[156:157], v[158:159]
	v_mov_b32_e32 v158, 0
	v_cvt_pk_bf16_f32 v155, v156, v157
	v_or_b32_e32 v156, 1, v182
	v_ashrrev_i32_e32 v157, 31, v156
	v_lshlrev_b64 v[156:157], 11, v[156:157]
	v_lshl_add_u64 v[156:157], s[18:19], 0, v[156:157]
	v_lshl_add_u64 v[186:187], v[156:157], 0, v[170:171]
	v_mov_b32_e32 v232, v154
	v_mov_b32_e32 v233, v155
	v_pk_fma_f32 v[154:155], v[92:93], v[140:141], v[144:145]
	v_mov_b32_e32 v156, 0
	v_pk_fma_f32 v[154:155], v[108:109], v[136:137], v[154:155]
	v_mov_b32_e32 v157, 0
	v_pk_fma_f32 v[154:155], v[124:125], v[128:129], v[154:155]
	v_mov_b32_e32 v159, 0
	v_pk_fma_f32 v[150:151], v[132:133], v[150:151], v[154:155]
	v_pk_fma_f32 v[154:155], v[94:95], v[142:143], v[146:147]
	v_cvt_pk_bf16_f32 v150, v150, v151
	v_pk_fma_f32 v[154:155], v[110:111], v[138:139], v[154:155]
	s_nop 0
	v_pk_fma_f32 v[154:155], v[126:127], v[130:131], v[154:155]
	s_nop 0
	v_pk_fma_f32 v[152:153], v[134:135], v[152:153], v[154:155]
	v_mov_b32_e32 v154, 0
	v_cvt_pk_bf16_f32 v151, v152, v153
	v_or_b32_e32 v152, 2, v182
	v_ashrrev_i32_e32 v153, 31, v152
	v_lshlrev_b64 v[152:153], 11, v[152:153]
	v_lshl_add_u64 v[152:153], s[18:19], 0, v[152:153]
	v_lshl_add_u64 v[188:189], v[152:153], 0, v[170:171]
	v_mov_b32_e32 v235, v150
	v_mov_b32_e32 v244, v151
	v_pk_fma_f32 v[150:151], v[78:79], v[142:143], v[146:147]
	v_pk_fma_f32 v[152:153], v[76:77], v[140:141], v[144:145]
	v_pk_fma_f32 v[150:151], v[94:95], v[138:139], v[150:151]
	v_pk_fma_f32 v[152:153], v[92:93], v[136:137], v[152:153]
	v_pk_fma_f32 v[150:151], v[110:111], v[130:131], v[150:151]
	v_pk_fma_f32 v[152:153], v[108:109], v[128:129], v[152:153]
	v_pk_fma_f32 v[150:151], v[126:127], v[134:135], v[150:151]
	v_pk_fma_f32 v[152:153], v[124:125], v[132:133], v[152:153]
	v_mov_b32_e32 v155, 0
	v_cvt_pk_bf16_f32 v152, v152, v153
	v_cvt_pk_bf16_f32 v153, v150, v151
	v_or_b32_e32 v150, 3, v182
	v_ashrrev_i32_e32 v151, 31, v150
	v_lshlrev_b64 v[150:151], 11, v[150:151]
	v_lshl_add_u64 v[150:151], s[18:19], 0, v[150:151]
	v_lshl_add_u64 v[190:191], v[150:151], 0, v[170:171]
	v_mov_b32_e32 v245, v152
	v_mov_b32_e32 v246, v153
	v_mov_b32_e32 v150, 0
	v_mov_b32_e32 v151, 0
	v_mov_b32_e32 v152, 0
	v_mov_b32_e32 v153, 0
	s_and_saveexec_b64 s[76:77], s[36:37]
	s_cbranch_execz .LBB0_1002
	ds_read_b128 v[148:151], v205 offset:3072
	ds_read_b128 v[156:159], v205 offset:4096
	ds_read_b128 v[152:155], v205 offset:5120
; #define LAS __attribute__((address_space(3)))
;     __device__ __forceinline__ void operator()(AccRef acc, const Unit& u, int wr, int wc, int fr, int fq) const {
;     ...
;         for (int bj = 0; bj < 2; ++bj)
; #pragma unroll
;             for (int n = 0; n < 2; ++n) {
;                 const int c0 = col0 + bj * 128 + 4 * n;
;                 const f32x4 w0 = *(const f32x4*)(cw + c0), w1 = *(const f32x4*)(cw + D + c0), w2 = *(const f32x4*)(cw + 2 * D + c0), w3 = *(const f32x4*)(cw + 3 * D + c0), bb = *(const f32x4*)(cb + c0);
; #pragma unroll
;                 for (int ai = 0; ai < 2; ++ai) {
;                     f32x4 h1 = (f32x4){0.f, 0.f, 0.f, 0.f}, h2 = h1, h3 = h1;
;                     const int pb = ai * 2 + wr - 1;
;                     if (pb >= 0 && fr == 0) { const LAS float* xp = xch + (pb * 3) * 256 + bj * 128 + clb + 4 * n; h1 = *(const LAS f32x4*)(xp); h2 = *(const LAS f32x4*)(xp + 256); h3 = *(const LAS f32x4*)(xp + 512); }
;                     float o[4][4];
; #pragma unroll
;                     for (int j = 0; j < 4; ++j) {
;                         const float v0 = acc[ai][bj][0][n][j], v1 = acc[ai][bj][1][n][j], v2 = acc[ai][bj][2][n][j], v3 = acc[ai][bj][3][n][j];
;                         const float p3 = dpp_upd<0x111>(h3[j], v3), p2 = dpp_upd<0x111>(h2[j], v2), p1 = dpp_upd<0x111>(h1[j], v1);
;                         o[0][j] = bb[j] + w3[j] * v0 + w2[j] * p3 + w1[j] * p2 + w0[j] * p1;
;                         o[1][j] = bb[j] + w3[j] * v1 + w2[j] * v0 + w1[j] * p3 + w0[j] * p2;
;                         o[2][j] = bb[j] + w3[j] * v2 + w2[j] * v1 + w1[j] * v0 + w0[j] * p3;
;                         o[3][j] = bb[j] + w3[j] * v3 + w2[j] * v2 + w1[j] * v1 + w0[j] * v0; }
; #pragma unroll
;                     for (int m = 0; m < 4; ++m) *(u32x2*)(REC + (size_t)(row0 + ai * 128 + m) * D + c0) = (u32x2){cvt_pk_bf16(o[m][0], o[m][1]), cvt_pk_bf16(o[m][2], o[m][3])};
;                 }
.LBB0_1002:
	s_or_b64 exec, exec, s[76:77]
	s_waitcnt lgkmcnt(0)
	v_mov_b32_dpp v152, v12 row_shr:1 row_mask:0xf bank_mask:0xf
	v_mov_b32_dpp v153, v13 row_shr:1 row_mask:0xf bank_mask:0xf
	v_pk_fma_f32 v[160:161], v[60:61], v[140:141], v[144:145]
	v_mov_b32_dpp v156, v28 row_shr:1 row_mask:0xf bank_mask:0xf
	v_mov_b32_dpp v157, v29 row_shr:1 row_mask:0xf bank_mask:0xf
	v_pk_fma_f32 v[160:161], v[136:137], v[152:153], v[160:161]
	v_mov_b32_dpp v148, v44 row_shr:1 row_mask:0xf bank_mask:0xf
	v_mov_b32_dpp v149, v45 row_shr:1 row_mask:0xf bank_mask:0xf
	v_pk_fma_f32 v[160:161], v[128:129], v[156:157], v[160:161]
	v_mov_b32_dpp v154, v14 row_shr:1 row_mask:0xf bank_mask:0xf
	v_mov_b32_dpp v155, v15 row_shr:1 row_mask:0xf bank_mask:0xf
	v_pk_fma_f32 v[148:149], v[132:133], v[148:149], v[160:161]
	v_pk_fma_f32 v[160:161], v[62:63], v[142:143], v[146:147]
	v_mov_b32_dpp v158, v30 row_shr:1 row_mask:0xf bank_mask:0xf
	v_mov_b32_dpp v159, v31 row_shr:1 row_mask:0xf bank_mask:0xf
	v_pk_fma_f32 v[160:161], v[138:139], v[154:155], v[160:161]
	v_mov_b32_dpp v150, v46 row_shr:1 row_mask:0xf bank_mask:0xf
	v_mov_b32_dpp v151, v47 row_shr:1 row_mask:0xf bank_mask:0xf
	v_pk_fma_f32 v[160:161], v[130:131], v[158:159], v[160:161]
	v_cvt_pk_bf16_f32 v148, v148, v149
	v_pk_fma_f32 v[150:151], v[134:135], v[150:151], v[160:161]
	v_mov_b32_e32 v193, v171
	v_cvt_pk_bf16_f32 v149, v150, v151
	v_add_co_u32_e32 v150, vcc, s6, v184
	v_lshl_add_u64 v[194:195], s[20:21], 0, v[192:193]
	s_nop 0
	v_addc_co_u32_e32 v151, vcc, 0, v185, vcc
	v_add_co_u32_e32 v160, vcc, s7, v184
	v_lshl_add_u64 v[192:193], s[22:23], 0, v[192:193]
	s_nop 0
	v_addc_co_u32_e32 v161, vcc, 0, v185, vcc
	v_mov_b32_e32 v247, v148
	v_mov_b32_e32 v248, v149
	v_pk_fma_f32 v[148:149], v[44:45], v[140:141], v[144:145]
	s_nop 0
	v_pk_fma_f32 v[148:149], v[60:61], v[136:137], v[148:149]
	s_nop 0
	v_pk_fma_f32 v[148:149], v[128:129], v[152:153], v[148:149]
	s_nop 0
	v_pk_fma_f32 v[148:149], v[132:133], v[156:157], v[148:149]
	v_pk_fma_f32 v[156:157], v[46:47], v[142:143], v[146:147]
	v_cvt_pk_bf16_f32 v148, v148, v149
	v_pk_fma_f32 v[156:157], v[62:63], v[138:139], v[156:157]
	s_nop 0
	v_pk_fma_f32 v[156:157], v[130:131], v[154:155], v[156:157]
	s_nop 0
	v_pk_fma_f32 v[156:157], v[134:135], v[158:159], v[156:157]
	v_mov_b32_e32 v158, 0
	v_cvt_pk_bf16_f32 v149, v156, v157
	v_mov_b32_e32 v249, v148
	v_mov_b32_e32 v250, v149
	v_pk_fma_f32 v[148:149], v[28:29], v[140:141], v[144:145]
	v_pk_fma_f32 v[140:141], v[12:13], v[140:141], v[144:145]
	v_pk_fma_f32 v[148:149], v[44:45], v[136:137], v[148:149]
	v_pk_fma_f32 v[136:137], v[28:29], v[136:137], v[140:141]
	v_pk_fma_f32 v[148:149], v[60:61], v[128:129], v[148:149]
	v_pk_fma_f32 v[150:151], v[30:31], v[142:143], v[146:147]
	v_pk_fma_f32 v[142:143], v[14:15], v[142:143], v[146:147]
	v_pk_fma_f32 v[128:129], v[44:45], v[128:129], v[136:137]
	v_pk_fma_f32 v[148:149], v[132:133], v[152:153], v[148:149]
	v_pk_fma_f32 v[150:151], v[46:47], v[138:139], v[150:151]
	v_pk_fma_f32 v[128:129], v[60:61], v[132:133], v[128:129]
	v_pk_fma_f32 v[132:133], v[30:31], v[138:139], v[142:143]
	v_pk_fma_f32 v[150:151], v[62:63], v[130:131], v[150:151]
	v_pk_fma_f32 v[130:131], v[46:47], v[130:131], v[132:133]
	v_pk_fma_f32 v[150:151], v[134:135], v[154:155], v[150:151]
	v_pk_fma_f32 v[130:131], v[62:63], v[134:135], v[130:131]
	v_cvt_pk_bf16_f32 v148, v148, v149
	v_cvt_pk_bf16_f32 v149, v150, v151
	v_cvt_pk_bf16_f32 v128, v128, v129
	v_cvt_pk_bf16_f32 v129, v130, v131
	v_mov_b32_e32 v251, v148
	v_mov_b32_e32 v253, v149
	v_mov_b32_e32 v254, v128
	v_mov_b32_e32 v255, v129
	v_lshl_or_b32 v140, v220, 2, 16
	global_load_dwordx4 v[128:131], v[194:195], off offset:16
	global_load_dwordx4 v[132:135], v140, s[38:39]
	global_load_dwordx4 v[136:139], v140, s[40:41]
	s_nop 0
	global_load_dwordx4 v[140:143], v140, s[42:43]
	s_nop 0
	global_load_dwordx4 v[144:147], v[192:193], off offset:16
	v_mov_b32_e32 v148, 0
	v_mov_b32_e32 v159, 0
	v_mov_b32_e32 v160, 0
	v_mov_b32_e32 v161, 0
	v_mov_b32_e32 v154, 0
	v_mov_b32_e32 v155, 0
	v_mov_b32_e32 v156, 0
	v_mov_b32_e32 v157, 0
	v_mov_b32_e32 v150, 0
	v_mov_b32_e32 v151, 0
	v_mov_b32_e32 v152, 0
	v_mov_b32_e32 v153, 0
	s_and_saveexec_b64 s[76:77], s[34:35]
	s_cbranch_execz .LBB0_1004
	ds_read_b128 v[158:161], v209
	ds_read_b128 v[154:157], v208
	ds_read_b128 v[150:153], v207
; #define LAS __attribute__((address_space(3)))
;     __device__ __forceinline__ void operator()(AccRef acc, const Unit& u, int wr, int wc, int fr, int fq) const {
;     ...
;         for (int bj = 0; bj < 2; ++bj)
; #pragma unroll
;             for (int n = 0; n < 2; ++n) {
;                 const int c0 = col0 + bj * 128 + 4 * n;
;                 const f32x4 w0 = *(const f32x4*)(cw + c0), w1 = *(const f32x4*)(cw + D + c0), w2 = *(const f32x4*)(cw + 2 * D + c0), w3 = *(const f32x4*)(cw + 3 * D + c0), bb = *(const f32x4*)(cb + c0);
; #pragma unroll
;                 for (int ai = 0; ai < 2; ++ai) {
;                     f32x4 h1 = (f32x4){0.f, 0.f, 0.f, 0.f}, h2 = h1, h3 = h1;
;                     const int pb = ai * 2 + wr - 1;
;                     if (pb >= 0 && fr == 0) { const LAS float* xp = xch + (pb * 3) * 256 + bj * 128 + clb + 4 * n; h1 = *(const LAS f32x4*)(xp); h2 = *(const LAS f32x4*)(xp + 256); h3 = *(const LAS f32x4*)(xp + 512); }
;                     float o[4][4];
; #pragma unroll
;                     for (int j = 0; j < 4; ++j) {
;                         const float v0 = acc[ai][bj][0][n][j], v1 = acc[ai][bj][1][n][j], v2 = acc[ai][bj][2][n][j], v3 = acc[ai][bj][3][n][j];
;                         const float p3 = dpp_upd<0x111>(h3[j], v3), p2 = dpp_upd<0x111>(h2[j], v2), p1 = dpp_upd<0x111>(h1[j], v1);
;                         o[0][j] = bb[j] + w3[j] * v0 + w2[j] * p3 + w1[j] * p2 + w0[j] * p1;
;                         o[1][j] = bb[j] + w3[j] * v1 + w2[j] * v0 + w1[j] * p3 + w0[j] * p2;
;                         o[2][j] = bb[j] + w3[j] * v2 + w2[j] * v1 + w1[j] * v0 + w0[j] * p3;
;                         o[3][j] = bb[j] + w3[j] * v3 + w2[j] * v2 + w1[j] * v1 + w0[j] * v0; }
; #pragma unroll
;                     for (int m = 0; m < 4; ++m) *(u32x2*)(REC + (size_t)(row0 + ai * 128 + m) * D + c0) = (u32x2){cvt_pk_bf16(o[m][0], o[m][1]), cvt_pk_bf16(o[m][2], o[m][3])};
;                 }
.LBB0_1004:
	s_or_b64 exec, exec, s[76:77]
	s_waitcnt lgkmcnt(0)
	v_mov_b32_dpp v150, v72 row_shr:1 row_mask:0xf bank_mask:0xf
	v_mov_b32_dpp v151, v73 row_shr:1 row_mask:0xf bank_mask:0xf
	s_waitcnt vmcnt(0)
	v_pk_fma_f32 v[196:197], v[120:121], v[140:141], v[144:145]
	v_mov_b32_dpp v154, v88 row_shr:1 row_mask:0xf bank_mask:0xf
	v_mov_b32_dpp v155, v89 row_shr:1 row_mask:0xf bank_mask:0xf
	v_pk_fma_f32 v[196:197], v[136:137], v[150:151], v[196:197]
	v_mov_b32_dpp v158, v104 row_shr:1 row_mask:0xf bank_mask:0xf
	v_mov_b32_dpp v159, v105 row_shr:1 row_mask:0xf bank_mask:0xf
	v_pk_fma_f32 v[196:197], v[132:133], v[154:155], v[196:197]
	v_mov_b32_dpp v152, v74 row_shr:1 row_mask:0xf bank_mask:0xf
	v_mov_b32_dpp v153, v75 row_shr:1 row_mask:0xf bank_mask:0xf
	v_pk_fma_f32 v[158:159], v[128:129], v[158:159], v[196:197]
	v_pk_fma_f32 v[196:197], v[122:123], v[142:143], v[146:147]
	v_mov_b32_dpp v156, v90 row_shr:1 row_mask:0xf bank_mask:0xf
	v_mov_b32_dpp v157, v91 row_shr:1 row_mask:0xf bank_mask:0xf
	v_pk_fma_f32 v[196:197], v[138:139], v[152:153], v[196:197]
	v_mov_b32_dpp v160, v106 row_shr:1 row_mask:0xf bank_mask:0xf
	v_mov_b32_dpp v161, v107 row_shr:1 row_mask:0xf bank_mask:0xf
	v_pk_fma_f32 v[196:197], v[134:135], v[156:157], v[196:197]
	v_cvt_pk_bf16_f32 v158, v158, v159
	v_pk_fma_f32 v[160:161], v[130:131], v[160:161], v[196:197]
	v_mov_b32_e32 v149, 0
	v_cvt_pk_bf16_f32 v159, v160, v161
	v_mov_b32_e32 v224, v183
	v_mov_b32_e32 v225, v221
	v_mov_b32_e32 v226, v158
	v_mov_b32_e32 v227, v159
	global_store_dwordx4 v[184:185], v[224:227], off
	v_pk_fma_f32 v[158:159], v[104:105], v[140:141], v[144:145]
	s_nop 0
	v_pk_fma_f32 v[158:159], v[120:121], v[136:137], v[158:159]
	s_nop 0
	v_pk_fma_f32 v[158:159], v[132:133], v[150:151], v[158:159]
	s_nop 0
	v_pk_fma_f32 v[154:155], v[128:129], v[154:155], v[158:159]
	v_pk_fma_f32 v[158:159], v[106:107], v[142:143], v[146:147]
	v_cvt_pk_bf16_f32 v154, v154, v155
	v_pk_fma_f32 v[158:159], v[122:123], v[138:139], v[158:159]
	s_nop 0
	v_pk_fma_f32 v[158:159], v[134:135], v[152:153], v[158:159]
	s_nop 0
	v_pk_fma_f32 v[156:157], v[130:131], v[156:157], v[158:159]
	v_mov_b32_e32 v158, 0
	v_cvt_pk_bf16_f32 v155, v156, v157
	v_mov_b32_e32 v228, v232
	v_mov_b32_e32 v229, v233
	v_mov_b32_e32 v230, v154
	v_mov_b32_e32 v231, v155
	global_store_dwordx4 v[186:187], v[228:231], off
	v_pk_fma_f32 v[154:155], v[88:89], v[140:141], v[144:145]
	v_mov_b32_e32 v156, 0
	v_pk_fma_f32 v[154:155], v[104:105], v[136:137], v[154:155]
	v_mov_b32_e32 v157, 0
	v_pk_fma_f32 v[154:155], v[120:121], v[132:133], v[154:155]
	v_mov_b32_e32 v159, 0
	v_pk_fma_f32 v[150:151], v[128:129], v[150:151], v[154:155]
	v_pk_fma_f32 v[154:155], v[90:91], v[142:143], v[146:147]
	v_cvt_pk_bf16_f32 v150, v150, v151
	v_pk_fma_f32 v[154:155], v[106:107], v[138:139], v[154:155]
	s_nop 0
	v_pk_fma_f32 v[154:155], v[122:123], v[134:135], v[154:155]
	s_nop 0
	v_pk_fma_f32 v[152:153], v[130:131], v[152:153], v[154:155]
	v_mov_b32_e32 v154, 0
	v_cvt_pk_bf16_f32 v151, v152, v153
	v_mov_b32_e32 v236, v235
	v_mov_b32_e32 v237, v244
	v_mov_b32_e32 v238, v150
	v_mov_b32_e32 v239, v151
	global_store_dwordx4 v[188:189], v[236:239], off
	v_pk_fma_f32 v[150:151], v[74:75], v[142:143], v[146:147]
	v_pk_fma_f32 v[152:153], v[72:73], v[140:141], v[144:145]
	v_pk_fma_f32 v[150:151], v[90:91], v[138:139], v[150:151]
	v_pk_fma_f32 v[152:153], v[88:89], v[136:137], v[152:153]
	v_pk_fma_f32 v[150:151], v[106:107], v[134:135], v[150:151]
	v_pk_fma_f32 v[152:153], v[104:105], v[132:133], v[152:153]
	v_pk_fma_f32 v[150:151], v[122:123], v[130:131], v[150:151]
	v_pk_fma_f32 v[152:153], v[120:121], v[128:129], v[152:153]
	v_mov_b32_e32 v155, 0
	v_cvt_pk_bf16_f32 v152, v152, v153
	v_cvt_pk_bf16_f32 v153, v150, v151
	v_mov_b32_e32 v240, v245
	v_mov_b32_e32 v241, v246
	v_mov_b32_e32 v242, v152
	v_mov_b32_e32 v243, v153
	global_store_dwordx4 v[190:191], v[240:243], off
	v_mov_b32_e32 v150, 0
	v_mov_b32_e32 v151, 0
	v_mov_b32_e32 v152, 0
	v_mov_b32_e32 v153, 0
	s_and_saveexec_b64 s[76:77], s[36:37]
	s_cbranch_execz .LBB0_1006
	ds_read_b128 v[148:151], v205 offset:3088
	ds_read_b128 v[156:159], v205 offset:4112
	ds_read_b128 v[152:155], v205 offset:5136
.LBB0_1006:
	s_or_b64 exec, exec, s[76:77]
	s_waitcnt lgkmcnt(0)
; #define LAS __attribute__((address_space(3)))
;     __device__ __forceinline__ void operator()(AccRef acc, const Unit& u, int wr, int wc, int fr, int fq) const {
;     ...
;         for (int bj = 0; bj < 2; ++bj)
; #pragma unroll
;             for (int n = 0; n < 2; ++n) {
;                 const int c0 = col0 + bj * 128 + 4 * n;
;                 const f32x4 w0 = *(const f32x4*)(cw + c0), w1 = *(const f32x4*)(cw + D + c0), w2 = *(const f32x4*)(cw + 2 * D + c0), w3 = *(const f32x4*)(cw + 3 * D + c0), bb = *(const f32x4*)(cb + c0);
; #pragma unroll
;                 for (int ai = 0; ai < 2; ++ai) {
;                     f32x4 h1 = (f32x4){0.f, 0.f, 0.f, 0.f}, h2 = h1, h3 = h1;
;                     const int pb = ai * 2 + wr - 1;
;                     if (pb >= 0 && fr == 0) { const LAS float* xp = xch + (pb * 3) * 256 + bj * 128 + clb + 4 * n; h1 = *(const LAS f32x4*)(xp); h2 = *(const LAS f32x4*)(xp + 256); h3 = *(const LAS f32x4*)(xp + 512); }
;                     float o[4][4];
; #pragma unroll
;                     for (int j = 0; j < 4; ++j) {
;                         const float v0 = acc[ai][bj][0][n][j], v1 = acc[ai][bj][1][n][j], v2 = acc[ai][bj][2][n][j], v3 = acc[ai][bj][3][n][j];
;                         const float p3 = dpp_upd<0x111>(h3[j], v3), p2 = dpp_upd<0x111>(h2[j], v2), p1 = dpp_upd<0x111>(h1[j], v1);
;                         o[0][j] = bb[j] + w3[j] * v0 + w2[j] * p3 + w1[j] * p2 + w0[j] * p1;
;                         o[1][j] = bb[j] + w3[j] * v1 + w2[j] * v0 + w1[j] * p3 + w0[j] * p2;
;                         o[2][j] = bb[j] + w3[j] * v2 + w2[j] * v1 + w1[j] * v0 + w0[j] * p3;
;                         o[3][j] = bb[j] + w3[j] * v3 + w2[j] * v2 + w1[j] * v1 + w0[j] * v0; }
; #pragma unroll
;                     for (int m = 0; m < 4; ++m) *(u32x2*)(REC + (size_t)(row0 + ai * 128 + m) * D + c0) = (u32x2){cvt_pk_bf16(o[m][0], o[m][1]), cvt_pk_bf16(o[m][2], o[m][3])};
;                 }
	v_mov_b32_dpp v152, v8 row_shr:1 row_mask:0xf bank_mask:0xf
	v_mov_b32_dpp v153, v9 row_shr:1 row_mask:0xf bank_mask:0xf
	v_pk_fma_f32 v[160:161], v[56:57], v[140:141], v[144:145]
	v_mov_b32_dpp v156, v24 row_shr:1 row_mask:0xf bank_mask:0xf
	v_mov_b32_dpp v157, v25 row_shr:1 row_mask:0xf bank_mask:0xf
	v_pk_fma_f32 v[160:161], v[136:137], v[152:153], v[160:161]
	v_mov_b32_dpp v148, v40 row_shr:1 row_mask:0xf bank_mask:0xf
	v_mov_b32_dpp v149, v41 row_shr:1 row_mask:0xf bank_mask:0xf
	v_pk_fma_f32 v[160:161], v[132:133], v[156:157], v[160:161]
	v_mov_b32_dpp v154, v10 row_shr:1 row_mask:0xf bank_mask:0xf
	v_mov_b32_dpp v155, v11 row_shr:1 row_mask:0xf bank_mask:0xf
	v_pk_fma_f32 v[148:149], v[128:129], v[148:149], v[160:161]
	v_pk_fma_f32 v[160:161], v[58:59], v[142:143], v[146:147]
	v_mov_b32_dpp v158, v26 row_shr:1 row_mask:0xf bank_mask:0xf
	v_mov_b32_dpp v159, v27 row_shr:1 row_mask:0xf bank_mask:0xf
	v_pk_fma_f32 v[160:161], v[138:139], v[154:155], v[160:161]
	v_mov_b32_dpp v150, v42 row_shr:1 row_mask:0xf bank_mask:0xf
	v_mov_b32_dpp v151, v43 row_shr:1 row_mask:0xf bank_mask:0xf
	v_pk_fma_f32 v[160:161], v[134:135], v[158:159], v[160:161]
	v_lshl_add_u64 v[202:203], v[184:185], 0, s[26:27]
	v_pk_fma_f32 v[150:151], v[130:131], v[150:151], v[160:161]
	v_cvt_pk_bf16_f32 v148, v148, v149
	v_cvt_pk_bf16_f32 v149, v150, v151
	v_mov_b32_e32 v224, v247
	v_mov_b32_e32 v225, v248
	v_mov_b32_e32 v226, v148
	v_mov_b32_e32 v227, v149
	global_store_dwordx4 v[202:203], v[224:227], off
	v_pk_fma_f32 v[148:149], v[40:41], v[140:141], v[144:145]
	v_pk_fma_f32 v[150:151], v[42:43], v[142:143], v[146:147]
	v_pk_fma_f32 v[148:149], v[56:57], v[136:137], v[148:149]
	v_pk_fma_f32 v[150:151], v[58:59], v[138:139], v[150:151]
	v_pk_fma_f32 v[148:149], v[132:133], v[152:153], v[148:149]
	v_pk_fma_f32 v[150:151], v[134:135], v[154:155], v[150:151]
	v_pk_fma_f32 v[148:149], v[128:129], v[156:157], v[148:149]
	v_pk_fma_f32 v[150:151], v[130:131], v[158:159], v[150:151]
	v_lshl_add_u64 v[200:201], v[184:185], 0, s[44:45]
	v_cvt_pk_bf16_f32 v148, v148, v149
	v_cvt_pk_bf16_f32 v149, v150, v151
	v_mov_b32_e32 v228, v249
	v_mov_b32_e32 v229, v250
	v_mov_b32_e32 v230, v148
	v_mov_b32_e32 v231, v149
	global_store_dwordx4 v[200:201], v[228:231], off
	v_pk_fma_f32 v[148:149], v[24:25], v[140:141], v[144:145]
	v_pk_fma_f32 v[140:141], v[8:9], v[140:141], v[144:145]
	v_pk_fma_f32 v[148:149], v[40:41], v[136:137], v[148:149]
	v_pk_fma_f32 v[136:137], v[24:25], v[136:137], v[140:141]
	v_pk_fma_f32 v[148:149], v[56:57], v[132:133], v[148:149]
	v_pk_fma_f32 v[150:151], v[26:27], v[142:143], v[146:147]
	v_pk_fma_f32 v[142:143], v[10:11], v[142:143], v[146:147]
	v_pk_fma_f32 v[132:133], v[40:41], v[132:133], v[136:137]
	v_pk_fma_f32 v[148:149], v[128:129], v[152:153], v[148:149]
	v_pk_fma_f32 v[150:151], v[42:43], v[138:139], v[150:151]
	v_pk_fma_f32 v[128:129], v[56:57], v[128:129], v[132:133]
	v_pk_fma_f32 v[132:133], v[26:27], v[138:139], v[142:143]
	v_pk_fma_f32 v[150:151], v[58:59], v[134:135], v[150:151]
	v_pk_fma_f32 v[132:133], v[42:43], v[134:135], v[132:133]
	v_pk_fma_f32 v[150:151], v[130:131], v[154:155], v[150:151]
	v_pk_fma_f32 v[130:131], v[58:59], v[130:131], v[132:133]
	v_lshl_add_u64 v[198:199], v[184:185], 0, s[46:47]
	v_lshl_add_u64 v[196:197], v[184:185], 0, s[48:49]
	v_cvt_pk_bf16_f32 v148, v148, v149
	v_cvt_pk_bf16_f32 v149, v150, v151
	v_cvt_pk_bf16_f32 v128, v128, v129
	v_cvt_pk_bf16_f32 v129, v130, v131
	v_mov_b32_e32 v236, v251
	v_mov_b32_e32 v237, v253
	v_mov_b32_e32 v238, v148
	v_mov_b32_e32 v239, v149
	global_store_dwordx4 v[198:199], v[236:239], off
	v_mov_b32_e32 v240, v254
	v_mov_b32_e32 v241, v255
	v_mov_b32_e32 v242, v128
	v_mov_b32_e32 v243, v129
	global_store_dwordx4 v[196:197], v[240:243], off
	v_lshl_or_b32 v140, v220, 2, v217
	global_load_dwordx4 v[128:131], v[194:195], off offset:512
	global_load_dwordx4 v[132:135], v140, s[38:39]
	global_load_dwordx4 v[136:139], v140, s[40:41]
	s_nop 0
	global_load_dwordx4 v[140:143], v140, s[42:43]
	s_nop 0
	global_load_dwordx4 v[144:147], v[192:193], off offset:512
	v_mov_b32_e32 v148, 0
	v_mov_b32_e32 v158, 0
	v_mov_b32_e32 v159, 0
	v_mov_b32_e32 v160, 0
	v_mov_b32_e32 v161, 0
	v_mov_b32_e32 v154, 0
	v_mov_b32_e32 v155, 0
	v_mov_b32_e32 v156, 0
	v_mov_b32_e32 v157, 0
	v_mov_b32_e32 v150, 0
	v_mov_b32_e32 v151, 0
	v_mov_b32_e32 v152, 0
	v_mov_b32_e32 v153, 0
	s_and_saveexec_b64 s[76:77], s[34:35]
	s_cbranch_execz .LBB0_1008
	ds_read_b128 v[158:161], v210
	ds_read_b128 v[154:157], v210 offset:1024
	ds_read_b128 v[150:153], v210 offset:2048
; #define LAS __attribute__((address_space(3)))
;     __device__ __forceinline__ void operator()(AccRef acc, const Unit& u, int wr, int wc, int fr, int fq) const {
;     ...
;         for (int bj = 0; bj < 2; ++bj)
; #pragma unroll
;             for (int n = 0; n < 2; ++n) {
;                 const int c0 = col0 + bj * 128 + 4 * n;
;                 const f32x4 w0 = *(const f32x4*)(cw + c0), w1 = *(const f32x4*)(cw + D + c0), w2 = *(const f32x4*)(cw + 2 * D + c0), w3 = *(const f32x4*)(cw + 3 * D + c0), bb = *(const f32x4*)(cb + c0);
; #pragma unroll
;                 for (int ai = 0; ai < 2; ++ai) {
;                     f32x4 h1 = (f32x4){0.f, 0.f, 0.f, 0.f}, h2 = h1, h3 = h1;
;                     const int pb = ai * 2 + wr - 1;
;                     if (pb >= 0 && fr == 0) { const LAS float* xp = xch + (pb * 3) * 256 + bj * 128 + clb + 4 * n; h1 = *(const LAS f32x4*)(xp); h2 = *(const LAS f32x4*)(xp + 256); h3 = *(const LAS f32x4*)(xp + 512); }
;                     float o[4][4];
; #pragma unroll
;                     for (int j = 0; j < 4; ++j) {
;                         const float v0 = acc[ai][bj][0][n][j], v1 = acc[ai][bj][1][n][j], v2 = acc[ai][bj][2][n][j], v3 = acc[ai][bj][3][n][j];
;                         const float p3 = dpp_upd<0x111>(h3[j], v3), p2 = dpp_upd<0x111>(h2[j], v2), p1 = dpp_upd<0x111>(h1[j], v1);
;                         o[0][j] = bb[j] + w3[j] * v0 + w2[j] * p3 + w1[j] * p2 + w0[j] * p1;
;                         o[1][j] = bb[j] + w3[j] * v1 + w2[j] * v0 + w1[j] * p3 + w0[j] * p2;
;                         o[2][j] = bb[j] + w3[j] * v2 + w2[j] * v1 + w1[j] * v0 + w0[j] * p3;
;                         o[3][j] = bb[j] + w3[j] * v3 + w2[j] * v2 + w1[j] * v1 + w0[j] * v0; }
; #pragma unroll
;                     for (int m = 0; m < 4; ++m) *(u32x2*)(REC + (size_t)(row0 + ai * 128 + m) * D + c0) = (u32x2){cvt_pk_bf16(o[m][0], o[m][1]), cvt_pk_bf16(o[m][2], o[m][3])};
;                 }
.LBB0_1008:
	s_or_b64 exec, exec, s[76:77]
	s_waitcnt lgkmcnt(0)
	v_mov_b32_dpp v150, v68 row_shr:1 row_mask:0xf bank_mask:0xf
	v_mov_b32_dpp v151, v69 row_shr:1 row_mask:0xf bank_mask:0xf
	s_waitcnt vmcnt(0)
	v_pk_fma_f32 v[222:223], v[116:117], v[140:141], v[144:145]
	v_mov_b32_dpp v154, v84 row_shr:1 row_mask:0xf bank_mask:0xf
	v_mov_b32_dpp v155, v85 row_shr:1 row_mask:0xf bank_mask:0xf
	v_pk_fma_f32 v[222:223], v[136:137], v[150:151], v[222:223]
	v_mov_b32_dpp v158, v100 row_shr:1 row_mask:0xf bank_mask:0xf
	v_mov_b32_dpp v159, v101 row_shr:1 row_mask:0xf bank_mask:0xf
	v_pk_fma_f32 v[222:223], v[132:133], v[154:155], v[222:223]
	v_mov_b32_dpp v152, v70 row_shr:1 row_mask:0xf bank_mask:0xf
	v_mov_b32_dpp v153, v71 row_shr:1 row_mask:0xf bank_mask:0xf
	v_pk_fma_f32 v[158:159], v[128:129], v[158:159], v[222:223]
	v_pk_fma_f32 v[222:223], v[118:119], v[142:143], v[146:147]
	v_mov_b32_dpp v156, v86 row_shr:1 row_mask:0xf bank_mask:0xf
	v_mov_b32_dpp v157, v87 row_shr:1 row_mask:0xf bank_mask:0xf
	v_pk_fma_f32 v[222:223], v[138:139], v[152:153], v[222:223]
	v_mov_b32_dpp v160, v102 row_shr:1 row_mask:0xf bank_mask:0xf
	v_mov_b32_dpp v161, v103 row_shr:1 row_mask:0xf bank_mask:0xf
	v_pk_fma_f32 v[222:223], v[134:135], v[156:157], v[222:223]
	v_cvt_pk_bf16_f32 v158, v158, v159
	v_pk_fma_f32 v[160:161], v[130:131], v[160:161], v[222:223]
	v_mov_b32_e32 v149, 0
	v_cvt_pk_bf16_f32 v159, v160, v161
	v_mov_b32_e32 v183, v158
	v_mov_b32_e32 v221, v159
	v_pk_fma_f32 v[158:159], v[100:101], v[140:141], v[144:145]
	s_nop 0
	v_pk_fma_f32 v[158:159], v[116:117], v[136:137], v[158:159]
	s_nop 0
	v_pk_fma_f32 v[158:159], v[132:133], v[150:151], v[158:159]
	s_nop 0
	v_pk_fma_f32 v[154:155], v[128:129], v[154:155], v[158:159]
	v_pk_fma_f32 v[158:159], v[102:103], v[142:143], v[146:147]
	v_cvt_pk_bf16_f32 v154, v154, v155
	v_pk_fma_f32 v[158:159], v[118:119], v[138:139], v[158:159]
	s_nop 0
	v_pk_fma_f32 v[158:159], v[134:135], v[152:153], v[158:159]
	s_nop 0
	v_pk_fma_f32 v[156:157], v[130:131], v[156:157], v[158:159]
	v_mov_b32_e32 v158, 0
	v_cvt_pk_bf16_f32 v155, v156, v157
	v_mov_b32_e32 v232, v154
	v_mov_b32_e32 v233, v155
	v_pk_fma_f32 v[154:155], v[84:85], v[140:141], v[144:145]
	v_mov_b32_e32 v156, 0
	v_pk_fma_f32 v[154:155], v[100:101], v[136:137], v[154:155]
	v_mov_b32_e32 v157, 0
	v_pk_fma_f32 v[154:155], v[116:117], v[132:133], v[154:155]
	v_mov_b32_e32 v159, 0
	v_pk_fma_f32 v[150:151], v[128:129], v[150:151], v[154:155]
	v_pk_fma_f32 v[154:155], v[86:87], v[142:143], v[146:147]
	v_cvt_pk_bf16_f32 v150, v150, v151
	v_pk_fma_f32 v[154:155], v[102:103], v[138:139], v[154:155]
	s_nop 0
	v_pk_fma_f32 v[154:155], v[118:119], v[134:135], v[154:155]
	s_nop 0
	v_pk_fma_f32 v[152:153], v[130:131], v[152:153], v[154:155]
	v_mov_b32_e32 v154, 0
	v_cvt_pk_bf16_f32 v151, v152, v153
	v_mov_b32_e32 v235, v150
	v_mov_b32_e32 v244, v151
	v_pk_fma_f32 v[150:151], v[70:71], v[142:143], v[146:147]
	v_pk_fma_f32 v[152:153], v[68:69], v[140:141], v[144:145]
	v_pk_fma_f32 v[150:151], v[86:87], v[138:139], v[150:151]
	v_pk_fma_f32 v[152:153], v[84:85], v[136:137], v[152:153]
	v_pk_fma_f32 v[150:151], v[102:103], v[134:135], v[150:151]
	v_pk_fma_f32 v[152:153], v[100:101], v[132:133], v[152:153]
	v_pk_fma_f32 v[150:151], v[118:119], v[130:131], v[150:151]
	v_pk_fma_f32 v[152:153], v[116:117], v[128:129], v[152:153]
	v_mov_b32_e32 v155, 0
	v_cvt_pk_bf16_f32 v152, v152, v153
	v_cvt_pk_bf16_f32 v153, v150, v151
	v_mov_b32_e32 v245, v152
	v_mov_b32_e32 v246, v153
	v_mov_b32_e32 v150, 0
	v_mov_b32_e32 v151, 0
	v_mov_b32_e32 v152, 0
	v_mov_b32_e32 v153, 0
	s_and_saveexec_b64 s[76:77], s[36:37]
	s_cbranch_execz .LBB0_1010
	ds_read_b128 v[148:151], v205 offset:3584
	ds_read_b128 v[156:159], v205 offset:4608
	ds_read_b128 v[152:155], v205 offset:5632
.LBB0_1010:
	s_or_b64 exec, exec, s[76:77]
	s_waitcnt lgkmcnt(0)
	v_mov_b32_dpp v152, v4 row_shr:1 row_mask:0xf bank_mask:0xf
	v_mov_b32_dpp v153, v5 row_shr:1 row_mask:0xf bank_mask:0xf
	v_pk_fma_f32 v[160:161], v[52:53], v[140:141], v[144:145]
	v_mov_b32_dpp v156, v20 row_shr:1 row_mask:0xf bank_mask:0xf
	v_mov_b32_dpp v157, v21 row_shr:1 row_mask:0xf bank_mask:0xf
	v_pk_fma_f32 v[160:161], v[136:137], v[152:153], v[160:161]
	v_mov_b32_dpp v148, v36 row_shr:1 row_mask:0xf bank_mask:0xf
	v_mov_b32_dpp v149, v37 row_shr:1 row_mask:0xf bank_mask:0xf
	v_pk_fma_f32 v[160:161], v[132:133], v[156:157], v[160:161]
	v_mov_b32_dpp v154, v6 row_shr:1 row_mask:0xf bank_mask:0xf
	v_mov_b32_dpp v155, v7 row_shr:1 row_mask:0xf bank_mask:0xf
	v_pk_fma_f32 v[148:149], v[128:129], v[148:149], v[160:161]
	v_pk_fma_f32 v[160:161], v[54:55], v[142:143], v[146:147]
	v_mov_b32_dpp v158, v22 row_shr:1 row_mask:0xf bank_mask:0xf
	v_mov_b32_dpp v159, v23 row_shr:1 row_mask:0xf bank_mask:0xf
	v_pk_fma_f32 v[160:161], v[138:139], v[154:155], v[160:161]
	v_mov_b32_dpp v150, v38 row_shr:1 row_mask:0xf bank_mask:0xf
	v_mov_b32_dpp v151, v39 row_shr:1 row_mask:0xf bank_mask:0xf
	v_pk_fma_f32 v[160:161], v[134:135], v[158:159], v[160:161]
	v_cvt_pk_bf16_f32 v148, v148, v149
	v_pk_fma_f32 v[150:151], v[130:131], v[150:151], v[160:161]
	v_mov_b32_e32 v160, 0
	v_cvt_pk_bf16_f32 v149, v150, v151
	v_mov_b32_e32 v247, v148
	v_mov_b32_e32 v248, v149
	v_pk_fma_f32 v[148:149], v[36:37], v[140:141], v[144:145]
	v_pk_fma_f32 v[150:151], v[38:39], v[142:143], v[146:147]
	v_pk_fma_f32 v[148:149], v[52:53], v[136:137], v[148:149]
	v_pk_fma_f32 v[150:151], v[54:55], v[138:139], v[150:151]
	v_pk_fma_f32 v[148:149], v[132:133], v[152:153], v[148:149]
	v_pk_fma_f32 v[150:151], v[134:135], v[154:155], v[150:151]
	v_pk_fma_f32 v[148:149], v[128:129], v[156:157], v[148:149]
; #define LAS __attribute__((address_space(3)))
;     __device__ __forceinline__ void operator()(AccRef acc, const Unit& u, int wr, int wc, int fr, int fq) const {
;     ...
;         for (int bj = 0; bj < 2; ++bj)
; #pragma unroll
;             for (int n = 0; n < 2; ++n) {
;                 const int c0 = col0 + bj * 128 + 4 * n;
;                 const f32x4 w0 = *(const f32x4*)(cw + c0), w1 = *(const f32x4*)(cw + D + c0), w2 = *(const f32x4*)(cw + 2 * D + c0), w3 = *(const f32x4*)(cw + 3 * D + c0), bb = *(const f32x4*)(cb + c0);
; #pragma unroll
;                 for (int ai = 0; ai < 2; ++ai) {
;                     f32x4 h1 = (f32x4){0.f, 0.f, 0.f, 0.f}, h2 = h1, h3 = h1;
;                     const int pb = ai * 2 + wr - 1;
;                     if (pb >= 0 && fr == 0) { const LAS float* xp = xch + (pb * 3) * 256 + bj * 128 + clb + 4 * n; h1 = *(const LAS f32x4*)(xp); h2 = *(const LAS f32x4*)(xp + 256); h3 = *(const LAS f32x4*)(xp + 512); }
;                     float o[4][4];
; #pragma unroll
;                     for (int j = 0; j < 4; ++j) {
;                         const float v0 = acc[ai][bj][0][n][j], v1 = acc[ai][bj][1][n][j], v2 = acc[ai][bj][2][n][j], v3 = acc[ai][bj][3][n][j];
;                         const float p3 = dpp_upd<0x111>(h3[j], v3), p2 = dpp_upd<0x111>(h2[j], v2), p1 = dpp_upd<0x111>(h1[j], v1);
;                         o[0][j] = bb[j] + w3[j] * v0 + w2[j] * p3 + w1[j] * p2 + w0[j] * p1;
;                         o[1][j] = bb[j] + w3[j] * v1 + w2[j] * v0 + w1[j] * p3 + w0[j] * p2;
;                         o[2][j] = bb[j] + w3[j] * v2 + w2[j] * v1 + w1[j] * v0 + w0[j] * p3;
;                         o[3][j] = bb[j] + w3[j] * v3 + w2[j] * v2 + w1[j] * v1 + w0[j] * v0; }
; #pragma unroll
;                     for (int m = 0; m < 4; ++m) *(u32x2*)(REC + (size_t)(row0 + ai * 128 + m) * D + c0) = (u32x2){cvt_pk_bf16(o[m][0], o[m][1]), cvt_pk_bf16(o[m][2], o[m][3])};
;                 }
	v_pk_fma_f32 v[150:151], v[130:131], v[158:159], v[150:151]
	v_cvt_pk_bf16_f32 v148, v148, v149
	v_cvt_pk_bf16_f32 v149, v150, v151
	v_mov_b32_e32 v249, v148
	v_mov_b32_e32 v250, v149
	v_pk_fma_f32 v[148:149], v[20:21], v[140:141], v[144:145]
	v_pk_fma_f32 v[140:141], v[4:5], v[140:141], v[144:145]
	v_pk_fma_f32 v[148:149], v[36:37], v[136:137], v[148:149]
	v_pk_fma_f32 v[136:137], v[20:21], v[136:137], v[140:141]
	v_pk_fma_f32 v[148:149], v[52:53], v[132:133], v[148:149]
	v_pk_fma_f32 v[150:151], v[22:23], v[142:143], v[146:147]
	v_pk_fma_f32 v[142:143], v[6:7], v[142:143], v[146:147]
	v_pk_fma_f32 v[132:133], v[36:37], v[132:133], v[136:137]
	v_pk_fma_f32 v[148:149], v[128:129], v[152:153], v[148:149]
	v_pk_fma_f32 v[150:151], v[38:39], v[138:139], v[150:151]
	v_pk_fma_f32 v[128:129], v[52:53], v[128:129], v[132:133]
	v_pk_fma_f32 v[132:133], v[22:23], v[138:139], v[142:143]
	v_pk_fma_f32 v[150:151], v[54:55], v[134:135], v[150:151]
	v_pk_fma_f32 v[132:133], v[38:39], v[134:135], v[132:133]
	v_pk_fma_f32 v[150:151], v[130:131], v[154:155], v[150:151]
	v_pk_fma_f32 v[130:131], v[54:55], v[130:131], v[132:133]
	v_cvt_pk_bf16_f32 v148, v148, v149
	v_cvt_pk_bf16_f32 v149, v150, v151
	v_cvt_pk_bf16_f32 v128, v128, v129
	v_cvt_pk_bf16_f32 v129, v130, v131
	v_mov_b32_e32 v251, v148
	v_mov_b32_e32 v253, v149
	v_mov_b32_e32 v254, v128
	v_mov_b32_e32 v255, v129
	v_lshl_or_b32 v140, v220, 2, v218
	global_load_dwordx4 v[128:131], v[194:195], off offset:528
	global_load_dwordx4 v[132:135], v140, s[38:39]
	global_load_dwordx4 v[136:139], v140, s[40:41]
	s_nop 0
	global_load_dwordx4 v[140:143], v140, s[42:43]
	s_nop 0
	global_load_dwordx4 v[144:147], v[192:193], off offset:528
	v_mov_b32_e32 v148, 0
	v_mov_b32_e32 v158, 0
	v_mov_b32_e32 v159, 0
	v_mov_b32_e32 v161, 0
	v_mov_b32_e32 v154, 0
	v_mov_b32_e32 v155, 0
	v_mov_b32_e32 v156, 0
	v_mov_b32_e32 v157, 0
	v_mov_b32_e32 v150, 0
	v_mov_b32_e32 v151, 0
	v_mov_b32_e32 v152, 0
	v_mov_b32_e32 v153, 0
	s_and_saveexec_b64 s[76:77], s[34:35]
	s_cbranch_execz .LBB0_1012
	ds_read_b128 v[158:161], v213
	ds_read_b128 v[154:157], v212
	ds_read_b128 v[150:153], v211
.LBB0_1012:
	s_or_b64 exec, exec, s[76:77]
	s_waitcnt lgkmcnt(0)
	v_mov_b32_dpp v150, v64 row_shr:1 row_mask:0xf bank_mask:0xf
	v_mov_b32_dpp v151, v65 row_shr:1 row_mask:0xf bank_mask:0xf
	s_waitcnt vmcnt(0)
	v_pk_fma_f32 v[192:193], v[112:113], v[140:141], v[144:145]
	v_mov_b32_dpp v154, v80 row_shr:1 row_mask:0xf bank_mask:0xf
	v_mov_b32_dpp v155, v81 row_shr:1 row_mask:0xf bank_mask:0xf
	v_pk_fma_f32 v[192:193], v[136:137], v[150:151], v[192:193]
	v_mov_b32_dpp v158, v96 row_shr:1 row_mask:0xf bank_mask:0xf
	v_mov_b32_dpp v159, v97 row_shr:1 row_mask:0xf bank_mask:0xf
	v_pk_fma_f32 v[192:193], v[132:133], v[154:155], v[192:193]
	v_mov_b32_dpp v152, v66 row_shr:1 row_mask:0xf bank_mask:0xf
	v_mov_b32_dpp v153, v67 row_shr:1 row_mask:0xf bank_mask:0xf
	v_pk_fma_f32 v[158:159], v[128:129], v[158:159], v[192:193]
	v_pk_fma_f32 v[192:193], v[114:115], v[142:143], v[146:147]
	v_mov_b32_dpp v156, v82 row_shr:1 row_mask:0xf bank_mask:0xf
	v_mov_b32_dpp v157, v83 row_shr:1 row_mask:0xf bank_mask:0xf
	v_pk_fma_f32 v[192:193], v[138:139], v[152:153], v[192:193]
	v_mov_b32_dpp v160, v98 row_shr:1 row_mask:0xf bank_mask:0xf
	v_mov_b32_dpp v161, v99 row_shr:1 row_mask:0xf bank_mask:0xf
	v_pk_fma_f32 v[192:193], v[134:135], v[156:157], v[192:193]
	v_cvt_pk_bf16_f32 v158, v158, v159
	v_pk_fma_f32 v[160:161], v[130:131], v[160:161], v[192:193]
	v_mov_b32_e32 v149, 0
	v_cvt_pk_bf16_f32 v159, v160, v161
	v_mov_b32_e32 v224, v183
	v_mov_b32_e32 v225, v221
	v_mov_b32_e32 v226, v158
	v_mov_b32_e32 v227, v159
	global_store_dwordx4 v[184:185], v[224:227], off offset:256
	v_pk_fma_f32 v[158:159], v[96:97], v[140:141], v[144:145]
	s_nop 0
	v_pk_fma_f32 v[158:159], v[112:113], v[136:137], v[158:159]
	s_nop 0
	v_pk_fma_f32 v[158:159], v[132:133], v[150:151], v[158:159]
	s_nop 0
	v_pk_fma_f32 v[154:155], v[128:129], v[154:155], v[158:159]
	v_pk_fma_f32 v[158:159], v[98:99], v[142:143], v[146:147]
	v_cvt_pk_bf16_f32 v154, v154, v155
	v_pk_fma_f32 v[158:159], v[114:115], v[138:139], v[158:159]
	s_nop 0
	v_pk_fma_f32 v[158:159], v[134:135], v[152:153], v[158:159]
	s_nop 0
	v_pk_fma_f32 v[156:157], v[130:131], v[156:157], v[158:159]
	v_mov_b32_e32 v158, 0
	v_cvt_pk_bf16_f32 v155, v156, v157
	v_mov_b32_e32 v228, v232
	v_mov_b32_e32 v229, v233
	v_mov_b32_e32 v230, v154
	v_mov_b32_e32 v231, v155
	global_store_dwordx4 v[186:187], v[228:231], off offset:256
	v_pk_fma_f32 v[154:155], v[80:81], v[140:141], v[144:145]
	v_mov_b32_e32 v156, 0
	v_pk_fma_f32 v[154:155], v[96:97], v[136:137], v[154:155]
	v_mov_b32_e32 v157, 0
	v_pk_fma_f32 v[154:155], v[112:113], v[132:133], v[154:155]
	v_mov_b32_e32 v159, 0
	v_pk_fma_f32 v[150:151], v[128:129], v[150:151], v[154:155]
	v_pk_fma_f32 v[154:155], v[82:83], v[142:143], v[146:147]
	v_cvt_pk_bf16_f32 v150, v150, v151
	v_pk_fma_f32 v[154:155], v[98:99], v[138:139], v[154:155]
	s_nop 0
	v_pk_fma_f32 v[154:155], v[114:115], v[134:135], v[154:155]
	s_nop 0
	v_pk_fma_f32 v[152:153], v[130:131], v[152:153], v[154:155]
	v_mov_b32_e32 v154, 0
	v_cvt_pk_bf16_f32 v151, v152, v153
	v_mov_b32_e32 v236, v235
	v_mov_b32_e32 v237, v244
	v_mov_b32_e32 v238, v150
	v_mov_b32_e32 v239, v151
	global_store_dwordx4 v[188:189], v[236:239], off offset:256
	v_pk_fma_f32 v[150:151], v[66:67], v[142:143], v[146:147]
	v_pk_fma_f32 v[152:153], v[64:65], v[140:141], v[144:145]
	v_pk_fma_f32 v[150:151], v[82:83], v[138:139], v[150:151]
	v_pk_fma_f32 v[152:153], v[80:81], v[136:137], v[152:153]
	v_pk_fma_f32 v[150:151], v[98:99], v[134:135], v[150:151]
	v_pk_fma_f32 v[152:153], v[96:97], v[132:133], v[152:153]
	v_pk_fma_f32 v[150:151], v[114:115], v[130:131], v[150:151]
	v_pk_fma_f32 v[152:153], v[112:113], v[128:129], v[152:153]
	v_mov_b32_e32 v155, 0
	v_cvt_pk_bf16_f32 v152, v152, v153
	v_cvt_pk_bf16_f32 v153, v150, v151
	v_mov_b32_e32 v240, v245
	v_mov_b32_e32 v241, v246
	v_mov_b32_e32 v242, v152
	v_mov_b32_e32 v243, v153
	global_store_dwordx4 v[190:191], v[240:243], off offset:256
	v_mov_b32_e32 v150, 0
	v_mov_b32_e32 v151, 0
	v_mov_b32_e32 v152, 0
	v_mov_b32_e32 v153, 0
	s_and_saveexec_b64 s[76:77], s[36:37]
	s_cbranch_execz .LBB0_1014
	ds_read_b128 v[148:151], v205 offset:3600
	ds_read_b128 v[156:159], v205 offset:4624
	ds_read_b128 v[152:155], v205 offset:5648
; #define LAS __attribute__((address_space(3)))
;     __device__ __forceinline__ void operator()(AccRef acc, const Unit& u, int wr, int wc, int fr, int fq) const {
;     ...
;         for (int bj = 0; bj < 2; ++bj)
; #pragma unroll
;             for (int n = 0; n < 2; ++n) {
;                 const int c0 = col0 + bj * 128 + 4 * n;
;                 const f32x4 w0 = *(const f32x4*)(cw + c0), w1 = *(const f32x4*)(cw + D + c0), w2 = *(const f32x4*)(cw + 2 * D + c0), w3 = *(const f32x4*)(cw + 3 * D + c0), bb = *(const f32x4*)(cb + c0);
; #pragma unroll
;                 for (int ai = 0; ai < 2; ++ai) {
;                     f32x4 h1 = (f32x4){0.f, 0.f, 0.f, 0.f}, h2 = h1, h3 = h1;
;                     const int pb = ai * 2 + wr - 1;
;                     if (pb >= 0 && fr == 0) { const LAS float* xp = xch + (pb * 3) * 256 + bj * 128 + clb + 4 * n; h1 = *(const LAS f32x4*)(xp); h2 = *(const LAS f32x4*)(xp + 256); h3 = *(const LAS f32x4*)(xp + 512); }
;                     float o[4][4];
; #pragma unroll
;                     for (int j = 0; j < 4; ++j) {
;                         const float v0 = acc[ai][bj][0][n][j], v1 = acc[ai][bj][1][n][j], v2 = acc[ai][bj][2][n][j], v3 = acc[ai][bj][3][n][j];
;                         const float p3 = dpp_upd<0x111>(h3[j], v3), p2 = dpp_upd<0x111>(h2[j], v2), p1 = dpp_upd<0x111>(h1[j], v1);
;                         o[0][j] = bb[j] + w3[j] * v0 + w2[j] * p3 + w1[j] * p2 + w0[j] * p1;
;                         o[1][j] = bb[j] + w3[j] * v1 + w2[j] * v0 + w1[j] * p3 + w0[j] * p2;
;                         o[2][j] = bb[j] + w3[j] * v2 + w2[j] * v1 + w1[j] * v0 + w0[j] * p3;
;                         o[3][j] = bb[j] + w3[j] * v3 + w2[j] * v2 + w1[j] * v1 + w0[j] * v0; }
; #pragma unroll
;                     for (int m = 0; m < 4; ++m) *(u32x2*)(REC + (size_t)(row0 + ai * 128 + m) * D + c0) = (u32x2){cvt_pk_bf16(o[m][0], o[m][1]), cvt_pk_bf16(o[m][2], o[m][3])};
;                 }
.LBB0_1014:
	s_or_b64 exec, exec, s[76:77]
	s_waitcnt lgkmcnt(0)
	v_mov_b32_dpp v152, v0 row_shr:1 row_mask:0xf bank_mask:0xf
	v_mov_b32_dpp v153, v1 row_shr:1 row_mask:0xf bank_mask:0xf
	v_pk_fma_f32 v[160:161], v[48:49], v[140:141], v[144:145]
	v_mov_b32_dpp v156, v16 row_shr:1 row_mask:0xf bank_mask:0xf
	v_mov_b32_dpp v157, v17 row_shr:1 row_mask:0xf bank_mask:0xf
	v_pk_fma_f32 v[160:161], v[136:137], v[152:153], v[160:161]
	v_mov_b32_dpp v148, v32 row_shr:1 row_mask:0xf bank_mask:0xf
	v_mov_b32_dpp v149, v33 row_shr:1 row_mask:0xf bank_mask:0xf
	v_pk_fma_f32 v[160:161], v[132:133], v[156:157], v[160:161]
	v_mov_b32_dpp v154, v2 row_shr:1 row_mask:0xf bank_mask:0xf
	v_mov_b32_dpp v155, v3 row_shr:1 row_mask:0xf bank_mask:0xf
	v_pk_fma_f32 v[148:149], v[128:129], v[148:149], v[160:161]
	v_pk_fma_f32 v[160:161], v[50:51], v[142:143], v[146:147]
	v_mov_b32_dpp v158, v18 row_shr:1 row_mask:0xf bank_mask:0xf
	v_mov_b32_dpp v159, v19 row_shr:1 row_mask:0xf bank_mask:0xf
	v_pk_fma_f32 v[160:161], v[138:139], v[154:155], v[160:161]
	v_mov_b32_dpp v150, v34 row_shr:1 row_mask:0xf bank_mask:0xf
	v_mov_b32_dpp v151, v35 row_shr:1 row_mask:0xf bank_mask:0xf
	v_pk_fma_f32 v[160:161], v[134:135], v[158:159], v[160:161]
	v_cvt_pk_bf16_f32 v148, v148, v149
	v_pk_fma_f32 v[150:151], v[130:131], v[150:151], v[160:161]
	s_mov_b64 s[80:81], 0
	v_cvt_pk_bf16_f32 v149, v150, v151
	v_mov_b32_e32 v224, v247
	v_mov_b32_e32 v225, v248
	v_mov_b32_e32 v226, v148
	v_mov_b32_e32 v227, v149
	global_store_dwordx4 v[202:203], v[224:227], off offset:256
	v_pk_fma_f32 v[148:149], v[32:33], v[140:141], v[144:145]
	v_pk_fma_f32 v[150:151], v[34:35], v[142:143], v[146:147]
	v_pk_fma_f32 v[148:149], v[48:49], v[136:137], v[148:149]
	v_pk_fma_f32 v[150:151], v[50:51], v[138:139], v[150:151]
	v_pk_fma_f32 v[148:149], v[132:133], v[152:153], v[148:149]
	v_pk_fma_f32 v[150:151], v[134:135], v[154:155], v[150:151]
	v_pk_fma_f32 v[148:149], v[128:129], v[156:157], v[148:149]
	v_pk_fma_f32 v[150:151], v[130:131], v[158:159], v[150:151]
	v_cvt_pk_bf16_f32 v148, v148, v149
	v_cvt_pk_bf16_f32 v149, v150, v151
	v_mov_b32_e32 v228, v249
	v_mov_b32_e32 v229, v250
	v_mov_b32_e32 v230, v148
	v_mov_b32_e32 v231, v149
	global_store_dwordx4 v[200:201], v[228:231], off offset:256
	v_pk_fma_f32 v[148:149], v[16:17], v[140:141], v[144:145]
	v_pk_fma_f32 v[140:141], v[0:1], v[140:141], v[144:145]
	v_pk_fma_f32 v[148:149], v[32:33], v[136:137], v[148:149]
	v_pk_fma_f32 v[136:137], v[16:17], v[136:137], v[140:141]
	v_pk_fma_f32 v[148:149], v[48:49], v[132:133], v[148:149]
	v_pk_fma_f32 v[150:151], v[18:19], v[142:143], v[146:147]
	v_pk_fma_f32 v[142:143], v[2:3], v[142:143], v[146:147]
	v_pk_fma_f32 v[132:133], v[32:33], v[132:133], v[136:137]
	v_pk_fma_f32 v[148:149], v[128:129], v[152:153], v[148:149]
	v_pk_fma_f32 v[150:151], v[34:35], v[138:139], v[150:151]
	v_pk_fma_f32 v[128:129], v[48:49], v[128:129], v[132:133]
	v_pk_fma_f32 v[132:133], v[18:19], v[138:139], v[142:143]
	v_pk_fma_f32 v[150:151], v[50:51], v[134:135], v[150:151]
	v_pk_fma_f32 v[132:133], v[34:35], v[134:135], v[132:133]
	v_pk_fma_f32 v[150:151], v[130:131], v[154:155], v[150:151]
	v_pk_fma_f32 v[130:131], v[50:51], v[130:131], v[132:133]
	v_cvt_pk_bf16_f32 v148, v148, v149
	v_cvt_pk_bf16_f32 v149, v150, v151
	v_cvt_pk_bf16_f32 v128, v128, v129
	v_cvt_pk_bf16_f32 v129, v130, v131
	v_mov_b32_e32 v236, v251
	v_mov_b32_e32 v237, v253
	v_mov_b32_e32 v238, v148
	v_mov_b32_e32 v239, v149
	global_store_dwordx4 v[198:199], v[236:239], off offset:256
	v_mov_b32_e32 v240, v254
	v_mov_b32_e32 v241, v255
	v_mov_b32_e32 v242, v128
	v_mov_b32_e32 v243, v129
	global_store_dwordx4 v[196:197], v[240:243], off offset:256
